# ATT2F: LDS-DMA issue of tile j-2 moved from loop top into the last PV MFMA gaps (comp waves); non-comp waves keep it
# speedup vs baseline: 1.0494x; 1.0031x over previous
; template <bool DIFF, bool FIXED, bool F32SRC> ...
;     ...
;         const int b2 = (buf >= 1) ? buf - 1 : 2;
;         if (j - 2 >= u.jlo) ATT_DMA(j - 2, b2);
;         }
;         const bool comp = (wact && j <= cq && j >= cq - win);
.LBB0_414:
	s_add_i32 s13, s25, 2
	s_cmp_le_i32 s13, s30
	s_cselect_b64 s[18:19], -1, 0
	s_and_b64 s[18:19], s[0:1], s[18:19]
	s_cmp_ge_i32 s13, s29
	s_cselect_b64 s[66:67], -1, 0
	s_and_b64 s[18:19], s[18:19], s[66:67]
	s_andn2_b64 vcc, exec, s[18:19]
	s_cbranch_vccz .LBB0_417
	s_andn2_b64 vcc, exec, s[16:17]
	s_cbranch_vccnz .Lnc_nodma
	s_ashr_i32 s13, s12, 31
	s_lshl_b64 s[18:19], s[12:13], 11
	s_add_u32 s66, s50, s18
	s_addc_u32 s67, s60, s19
	s_add_u32 s18, s63, s18
	s_addc_u32 s19, s64, s19
	s_lshl_b32 s13, s28, 15
	s_addk_i32 s13, 0x8000
	s_cmp_gt_i32 s28, 0
	s_cselect_b32 s13, s13, 0x10000
	s_add_i32 s13, s51, s13
	v_lshl_add_u64 v[66:67], v[136:137], 1, s[66:67]
	s_mov_b32 m0, s13
	s_nop 0
	global_load_lds_dwordx4 v[66:67], off
	v_lshl_add_u64 v[66:67], v[138:139], 1, s[18:19]
	s_add_i32 m0, s13, 0x4000
	s_nop 0
	global_load_lds_dwordx4 v[66:67], off
	v_lshl_add_u64 v[66:67], v[140:141], 1, s[66:67]
	s_add_i32 m0, s13, 0x400
	s_nop 0
	global_load_lds_dwordx4 v[66:67], off
	v_lshl_add_u64 v[66:67], v[142:143], 1, s[18:19]
	s_add_i32 m0, s13, 0x4400
	s_nop 0
	global_load_lds_dwordx4 v[66:67], off
	s_add_i32 s13, s25, 2
.Lnc_nodma:
	s_andn2_b64 vcc, exec, s[16:17]
	s_mov_b64 s[16:17], -1
	s_cbranch_vccz .LBB0_422

; #define LAS __attribute__((address_space(3)))
; template <bool DIFF, bool FIXED, bool F32SRC> ...
;     ...
;             for (int ks = 0; ks < 2; ++ks) { a0 = MFMA32(kf0[ks], qf[ks], a0); a1 = MFMA32(kf1[ks], qf[ks], a1); }
;             __builtin_amdgcn_sched_barrier(0);
; #pragma unroll
;             for (int ks = 0; ks < 2; ++ks) { kf0[ks] = *(const LAS bf16x8*)(kb + koff[ks + 2]); kf1[ks] = *(const LAS bf16x8*)(kb + koff[ks + 2] + 32 * RB); }
;             __builtin_amdgcn_sched_barrier(0);
; #pragma unroll
;             for (int ks = 0; ks < 2; ++ks) { a0 = MFMA32(kf0[ks], qf[ks + 2], a0); a1 = MFMA32(kf1[ks], qf[ks + 2], a1); }
;             __builtin_amdgcn_sched_barrier(0);
;             bf16x8 vf[4];
;     ...
;             if (!FIXED) {
;             float mx = fmaxf(fmaxf(a0[0], a1[0]), fmaxf(a0[1], a1[1]));
; #pragma unroll
;             for (int r = 2; r < 16; r += 2) mx = fmaxf(fmaxf(mx, fmaxf(a0[r], a1[r])), fmaxf(a0[r + 1], a1[r + 1]));
;             mx = x32_max(mx);
;             if (__any(mx > 0.f)) {
;                 const float dl = fmaxf(mx, 0.f), al = __builtin_amdgcn_exp2f(-dl);
;                 lrun *= al; mrun += dl;
; #pragma unroll
;                 for (int r = 0; r < 16; ++r) { a0[r] -= dl; a1[r] -= dl; }
; #pragma unroll
;                 for (int db = 0; db < NDB; ++db)
; #pragma unroll
;                     for (int r = 0; r < 16; ++r) o[db][r] *= al;
;             }
;             }
;             float ls = 0.f;
; #pragma unroll
;             for (int r = 0; r < 16; ++r) { a0[r] = __builtin_amdgcn_exp2f(a0[r]); a1[r] = __builtin_amdgcn_exp2f(a1[r]); ls += a0[r] + a1[r]; }
;             lrun += ls;
;             bf16x8 pf[4];
; #pragma unroll
;             for (int ks = 0; ks < 4; ++ks) { u32x4 p;
; #pragma unroll
;                 for (int e = 0; e < 4; ++e) p[e] = (ks < 2) ? cvt_pk_bf16(a0[8 * ks + 2 * e], a0[8 * ks + 2 * e + 1]) : cvt_pk_bf16(a1[8 * (ks - 2) + 2 * e], a1[8 * (ks - 2) + 2 * e + 1]);
;                 pf[ks] = __builtin_bit_cast(bf16x8, p); }
; #pragma unroll
;             for (int db = 0; db < NDB; ++db) {
;                 ATT_VLOAD(vf, db);
;                 __builtin_amdgcn_sched_barrier(0);
; #pragma unroll
;                 for (int ks = 0; ks < 4; ++ks) o[db] = MFMA32(vf[ks], pf[ks], o[db]);
;                 __builtin_amdgcn_sched_barrier(0);
;             }
.LBB0_421:
	s_waitcnt lgkmcnt(4)
	v_mfma_f32_32x32x16_bf16 v[66:81], v[114:117], v[98:101], v[66:81]
	v_mfma_f32_32x32x16_bf16 v[66:81], v[118:121], v[102:105], v[66:81]
	v_mfma_f32_32x32x16_bf16 v[66:81], v[122:125], v[106:109], v[66:81]
	v_mfma_f32_32x32x16_bf16 v[66:81], v[126:129], v[110:113], v[66:81]
	v_add_u32_e32 v0, s66, v225
	ds_read_b64_tr_b16 v[114:115], v0 offset:16384
	ds_read_b64_tr_b16 v[116:117], v0 offset:18432
	ds_read_b64_tr_b16 v[118:119], v0 offset:16896
	ds_read_b64_tr_b16 v[120:121], v0 offset:18944
	ds_read_b64_tr_b16 v[122:123], v0 offset:17408
	ds_read_b64_tr_b16 v[124:125], v0 offset:19456
	ds_read_b64_tr_b16 v[126:127], v0 offset:17920
	ds_read_b64_tr_b16 v[128:129], v0 offset:19968
	s_waitcnt lgkmcnt(8)
	v_mfma_f32_32x32x16_bf16 v[82:97], v[146:149], v[98:101], v[82:97]
	s_nop 1
	v_exp_f32_e32 v66, v66
	v_exp_f32_e32 v67, v67
	v_exp_f32_e32 v68, v68
	v_mfma_f32_32x32x16_bf16 v[82:97], v[150:153], v[102:105], v[82:97]
	v_exp_f32_e32 v69, v69
	v_exp_f32_e32 v70, v70
	v_exp_f32_e32 v71, v71
	v_mfma_f32_32x32x16_bf16 v[82:97], v[154:157], v[106:109], v[82:97]
	v_exp_f32_e32 v72, v72
	v_exp_f32_e32 v73, v73
	v_add_f32_e32 v228, v66, v67
	v_add_f32_e32 v229, v68, v69
	v_cvt_pk_bf16_f32 v66, v66, v67
	v_mfma_f32_32x32x16_bf16 v[82:97], v[158:161], v[110:113], v[82:97]
	v_add_f32_e32 v228, v228, v70
	v_add_f32_e32 v229, v229, v71
	v_cvt_pk_bf16_f32 v67, v68, v69
	v_add_f32_e32 v228, v228, v72
	v_add_f32_e32 v229, v229, v73
	v_cvt_pk_bf16_f32 v68, v70, v71
	v_cvt_pk_bf16_f32 v69, v72, v73
	s_waitcnt lgkmcnt(7)
	ds_read_b64_tr_b16 v[146:147], v0 offset:20480
	ds_read_b64_tr_b16 v[148:149], v0 offset:22528
	ds_read_b64_tr_b16 v[150:151], v0 offset:20992
	ds_read_b64_tr_b16 v[152:153], v0 offset:23040
	ds_read_b64_tr_b16 v[154:155], v0 offset:21504
	ds_read_b64_tr_b16 v[156:157], v0 offset:23552
	ds_read_b64_tr_b16 v[158:159], v0 offset:22016
	ds_read_b64_tr_b16 v[160:161], v0 offset:24064
	s_waitcnt lgkmcnt(8)
	v_mfma_f32_32x32x16_bf16 v[50:65], v[114:117], v[66:69], v[50:65]
	v_exp_f32_e32 v74, v74
	v_exp_f32_e32 v75, v75
	v_exp_f32_e32 v76, v76
	v_mfma_f32_32x32x16_bf16 v[34:49], v[118:121], v[66:69], v[34:49]
	v_exp_f32_e32 v77, v77
	v_exp_f32_e32 v78, v78
	v_add_f32_e32 v228, v228, v74
	v_add_f32_e32 v229, v229, v75
	v_cvt_pk_bf16_f32 v70, v74, v75
	v_mfma_f32_32x32x16_bf16 v[18:33], v[122:125], v[66:69], v[18:33]
	v_exp_f32_e32 v79, v79
	v_exp_f32_e32 v80, v80
	v_add_f32_e32 v228, v228, v76
	v_add_f32_e32 v229, v229, v77
	v_cvt_pk_bf16_f32 v71, v76, v77
	v_mfma_f32_32x32x16_bf16 v[2:17], v[126:129], v[66:69], v[2:17]
	v_exp_f32_e32 v81, v81
	v_add_f32_e32 v228, v228, v78
	v_add_f32_e32 v229, v229, v79
	v_cvt_pk_bf16_f32 v72, v78, v79
	v_add_f32_e32 v228, v228, v80
	v_add_f32_e32 v229, v229, v81
	v_cvt_pk_bf16_f32 v73, v80, v81
	s_waitcnt lgkmcnt(7)
	ds_read_b64_tr_b16 v[114:115], v0 offset:24576
	ds_read_b64_tr_b16 v[116:117], v0 offset:26624
	ds_read_b64_tr_b16 v[118:119], v0 offset:25088
	ds_read_b64_tr_b16 v[120:121], v0 offset:27136
	ds_read_b64_tr_b16 v[122:123], v0 offset:25600
	ds_read_b64_tr_b16 v[124:125], v0 offset:27648
	ds_read_b64_tr_b16 v[126:127], v0 offset:26112
	ds_read_b64_tr_b16 v[128:129], v0 offset:28160
	s_waitcnt lgkmcnt(8)
	v_mfma_f32_32x32x16_bf16 v[50:65], v[146:149], v[70:73], v[50:65]
	v_exp_f32_e32 v82, v82
	v_exp_f32_e32 v83, v83
	v_exp_f32_e32 v84, v84
	v_mfma_f32_32x32x16_bf16 v[34:49], v[150:153], v[70:73], v[34:49]
	v_exp_f32_e32 v85, v85
	v_exp_f32_e32 v86, v86
	v_add_f32_e32 v228, v228, v82
	v_add_f32_e32 v229, v229, v83
	v_cvt_pk_bf16_f32 v74, v82, v83
	v_mfma_f32_32x32x16_bf16 v[18:33], v[154:157], v[70:73], v[18:33]
	v_exp_f32_e32 v87, v87
	v_exp_f32_e32 v88, v88
	v_add_f32_e32 v228, v228, v84
	v_add_f32_e32 v229, v229, v85
	v_cvt_pk_bf16_f32 v75, v84, v85
	v_mfma_f32_32x32x16_bf16 v[2:17], v[158:161], v[70:73], v[2:17]
	v_exp_f32_e32 v89, v89
	v_add_f32_e32 v228, v228, v86
	v_add_f32_e32 v229, v229, v87
	v_cvt_pk_bf16_f32 v76, v86, v87
	v_add_f32_e32 v228, v228, v88
	v_add_f32_e32 v229, v229, v89
	v_cvt_pk_bf16_f32 v77, v88, v89
	s_waitcnt lgkmcnt(7)
	ds_read_b64_tr_b16 v[146:147], v0 offset:28672
	ds_read_b64_tr_b16 v[148:149], v0 offset:30720
	ds_read_b64_tr_b16 v[150:151], v0 offset:29184
	ds_read_b64_tr_b16 v[152:153], v0 offset:31232
	ds_read_b64_tr_b16 v[154:155], v0 offset:29696
	ds_read_b64_tr_b16 v[156:157], v0 offset:31744
	ds_read_b64_tr_b16 v[158:159], v0 offset:30208
	ds_read_b64_tr_b16 v[160:161], v0 offset:32256
	s_waitcnt lgkmcnt(8)
	v_mfma_f32_32x32x16_bf16 v[50:65], v[114:117], v[74:77], v[50:65]
	v_exp_f32_e32 v90, v90
	v_exp_f32_e32 v91, v91
	v_exp_f32_e32 v92, v92
	v_mfma_f32_32x32x16_bf16 v[34:49], v[118:121], v[74:77], v[34:49]
	v_exp_f32_e32 v93, v93
	v_exp_f32_e32 v94, v94
	v_add_f32_e32 v228, v228, v90
	v_add_f32_e32 v229, v229, v91
	v_cvt_pk_bf16_f32 v78, v90, v91
	v_mfma_f32_32x32x16_bf16 v[18:33], v[122:125], v[74:77], v[18:33]
	v_exp_f32_e32 v95, v95
	v_exp_f32_e32 v96, v96
	v_add_f32_e32 v228, v228, v92
	v_add_f32_e32 v229, v229, v93
	v_cvt_pk_bf16_f32 v79, v92, v93
	v_mfma_f32_32x32x16_bf16 v[2:17], v[126:129], v[74:77], v[2:17]
	v_exp_f32_e32 v97, v97
	v_add_f32_e32 v228, v228, v94
	v_add_f32_e32 v229, v229, v95
	v_cvt_pk_bf16_f32 v80, v94, v95
	v_add_f32_e32 v228, v228, v96
	v_add_f32_e32 v229, v229, v97
	v_cvt_pk_bf16_f32 v81, v96, v97
	s_waitcnt lgkmcnt(0)
	v_add_f32_e32 v228, v228, v229
	s_andn2_b64 vcc, exec, s[16:17]
	s_cbranch_vccnz .Lpv3_nodma
	v_mfma_f32_32x32x16_bf16 v[50:65], v[146:149], v[78:81], v[50:65]
	v_add_f32_e32 v219, v219, v228
	s_ashr_i32 s13, s12, 31
	s_lshl_b64 s[18:19], s[12:13], 11
	s_add_u32 s66, s50, s18
	s_addc_u32 s67, s60, s19
	s_add_u32 s18, s63, s18
	s_addc_u32 s19, s64, s19
	s_lshl_b32 s13, s28, 15
	s_addk_i32 s13, 0x8000
	s_cmp_gt_i32 s28, 0
	s_cselect_b32 s13, s13, 0x10000
	s_add_i32 s13, s51, s13
	v_lshl_add_u64 v[230:231], v[136:137], 1, s[66:67]
	s_mov_b32 m0, s13
	s_nop 0
	global_load_lds_dwordx4 v[230:231], off
	v_mfma_f32_32x32x16_bf16 v[34:49], v[150:153], v[78:81], v[34:49]
	v_lshl_add_u64 v[230:231], v[138:139], 1, s[18:19]
	s_add_i32 m0, s13, 0x4000
	s_nop 0
	global_load_lds_dwordx4 v[230:231], off
	v_mfma_f32_32x32x16_bf16 v[18:33], v[154:157], v[78:81], v[18:33]
	v_lshl_add_u64 v[230:231], v[140:141], 1, s[66:67]
	s_add_i32 m0, s13, 0x400
	s_nop 0
	global_load_lds_dwordx4 v[230:231], off
	v_mfma_f32_32x32x16_bf16 v[2:17], v[158:161], v[78:81], v[2:17]
	v_lshl_add_u64 v[230:231], v[142:143], 1, s[18:19]
	s_add_i32 m0, s13, 0x4400
	s_nop 0
	global_load_lds_dwordx4 v[230:231], off
	s_add_i32 s13, s25, 2
	s_branch .Lpv3_done
.Lpv3_nodma:
	v_mfma_f32_32x32x16_bf16 v[50:65], v[146:149], v[78:81], v[50:65]
	v_add_f32_e32 v219, v219, v228
	v_mfma_f32_32x32x16_bf16 v[34:49], v[150:153], v[78:81], v[34:49]
	v_mfma_f32_32x32x16_bf16 v[18:33], v[154:157], v[78:81], v[18:33]
	v_mfma_f32_32x32x16_bf16 v[2:17], v[158:161], v[78:81], v[2:17]
.Lpv3_done:
	s_andn2_b64 vcc, exec, s[16:17]
	s_mov_b64 s[16:17], -1
	s_cbranch_vccnz .LBB0_416
